# grid barrier: released workgroups poll the cross-XCD generation word directly instead of waiting for their XCD leader's second-level release (one hop less after the last arrival)
# speedup vs baseline: 1.0162x; 1.0053x over previous
.LBB0_198:
	s_or_b64 exec, exec, s[8:9]
	v_cvt_f32_u32_e32 v4, v2
	s_waitcnt vmcnt(0)
	v_readfirstlane_b32 s6, v3
	v_sub_u32_e32 v3, 0, v2
	v_rcp_iflag_f32_e32 v4, v4
	v_add_u32_e32 v5, s6, v1
	v_mul_f32_e32 v4, 0x4f7ffffe, v4
	v_cvt_u32_f32_e32 v4, v4
	v_mul_lo_u32 v1, v3, v4
	v_mul_hi_u32 v1, v4, v1
	v_add_u32_e32 v1, v4, v1
	v_mul_hi_u32 v1, v5, v1
	v_mul_lo_u32 v3, v1, v2
	v_sub_u32_e32 v3, v5, v3
	v_add_u32_e32 v4, 1, v1
	v_cmp_ge_u32_e32 vcc, v3, v2
	s_nop 1
	v_cndmask_b32_e32 v1, v1, v4, vcc
	v_sub_u32_e32 v4, v3, v2
	v_cndmask_b32_e32 v3, v3, v4, vcc
	v_add_u32_e32 v4, 1, v1
	v_cmp_ge_u32_e32 vcc, v3, v2
	v_add_u32_e32 v3, 1, v5
	s_nop 0
	v_cndmask_b32_e32 v1, v1, v4, vcc
	v_mul_lo_u32 v4, v2, v1
	v_add_u32_e32 v2, v4, v2
	v_cmp_ne_u32_e32 vcc, v3, v2
	s_and_saveexec_b64 s[6:7], vcc
	s_xor_b64 s[6:7], exec, s[6:7]
	s_cbranch_execz .LBB0_212
	s_waitcnt lgkmcnt(0)
	v_readlane_b32 s10, v254, 39
	v_readlane_b32 s11, v254, 40
	s_nop 4
	global_load_dword v0, v129, s[10:11] sc1
	s_waitcnt vmcnt(0)
	v_cmp_eq_u32_e32 vcc, v0, v1
	s_and_saveexec_b64 s[8:9], vcc
	s_cbranch_execz .LBB0_211
	s_mov_b32 s22, 1
	s_mov_b64 s[12:13], 0
	s_branch .LBB0_202

.LBB0_1146:
	s_or_b64 exec, exec, s[6:7]
	v_cvt_f32_u32_e32 v4, v2
	s_waitcnt vmcnt(0)
	v_readfirstlane_b32 s4, v3
	v_sub_u32_e32 v3, 0, v2
	v_rcp_iflag_f32_e32 v4, v4
	v_add_u32_e32 v5, s4, v1
	v_mul_f32_e32 v4, 0x4f7ffffe, v4
	v_cvt_u32_f32_e32 v4, v4
	v_mul_lo_u32 v1, v3, v4
	v_mul_hi_u32 v1, v4, v1
	v_add_u32_e32 v1, v4, v1
	v_mul_hi_u32 v1, v5, v1
	v_mul_lo_u32 v3, v1, v2
	v_sub_u32_e32 v3, v5, v3
	v_add_u32_e32 v4, 1, v1
	v_cmp_ge_u32_e32 vcc, v3, v2
	s_nop 1
	v_cndmask_b32_e32 v1, v1, v4, vcc
	v_sub_u32_e32 v4, v3, v2
	v_cndmask_b32_e32 v3, v3, v4, vcc
	v_add_u32_e32 v4, 1, v1
	v_cmp_ge_u32_e32 vcc, v3, v2
	v_add_u32_e32 v3, 1, v5
	s_nop 0
	v_cndmask_b32_e32 v1, v1, v4, vcc
	v_mul_lo_u32 v4, v2, v1
	v_add_u32_e32 v2, v4, v2
	v_cmp_ne_u32_e32 vcc, v3, v2
	s_and_saveexec_b64 s[4:5], vcc
	s_xor_b64 s[4:5], exec, s[4:5]
	s_cbranch_execz .LBB0_1160
	s_waitcnt lgkmcnt(0)
	v_readlane_b32 s8, v254, 39
	v_readlane_b32 s9, v254, 40
	s_nop 4
	global_load_dword v0, v129, s[8:9] sc1
	s_waitcnt vmcnt(0)
	v_cmp_eq_u32_e32 vcc, v0, v1
	s_and_saveexec_b64 s[6:7], vcc
	s_cbranch_execz .LBB0_1159
	s_mov_b32 s20, 1
	s_mov_b64 s[10:11], 0
	s_branch .LBB0_1150
